# v19 + hot-address relief: XCC-mask prefetch issued by one lane per WG; layer-1 in-proj epilogue guard counter replicated x8 (one copy per wave)
# baseline (speedup 1.0000x reference)
;     __device__ bool next(int i, Unit& u) const {
;         const long L = (long)i * G + c; if (L >= nwg) return false;
;         int wgid = (int)L; { const int q = nwg / NXCD, r = nwg % NXCD, xcd = wgid % NXCD, off = wgid / NXCD; wgid = (xcd < r ? xcd * (q + 1) : r * (q + 1) + (xcd - r) * q) + off; }
;         const int nig = WGM * nN, gid = wgid / nig, fm = gid * WGM, gsz = (nM - fm) < WGM ? (nM - fm) : WGM;
;         u.pm = fm + ((wgid % nig) % gsz); u.pn = (wgid % nig) / gsz; return true;
; __global__ void __launch_bounds__(NTHREADS, 2) mk_fwd(Params P) {
;     ...
;     if (IN(1)) {
;         pg8::Gemm g{SLOTA, WINA, MTOK, 6144, 2048, 1 << 30, 0}; pg8::StaticOrder S; S.init(MTOK, 6144, G, bid);
;         EpiL0In E{Ub, GVb, STATS};
;         pg8::gemm_phase<EpiL0In, true>(lds, g, S, E);
.LBB0_143:
	s_and_saveexec_b64 s[100:101], s[12:13]
	s_and_b32 s98, s2, 7
	s_lshl_b32 s98, s98, 6
	s_add_i32 s98, s98, 0x8008
	v_mov_b32_e32 v255, s98
	global_load_dword v255, v255, s[54:55] sc1
	s_or_b64 exec, exec, s[100:101]
	s_waitcnt lgkmcnt(0)
	s_add_u32 s16, s40, 0x3a00000
	s_addc_u32 s17, s41, 0
	s_add_u32 s20, s40, 0x4000000
	s_addc_u32 s21, s41, 0
	s_add_u32 s8, s40, 0x8800000
	s_addc_u32 s9, s41, 0
	s_add_u32 s10, s40, 0xa800000
	s_addc_u32 s11, s41, 0
	s_cmp_lt_i32 s42, 2
	s_cselect_b64 s[4:5], -1, 0
	s_and_b64 s[0:1], s[4:5], s[0:1]
	s_andn2_b64 vcc, exec, s[0:1]
	s_cbranch_vccnz .LBB0_182
	s_cmpk_lt_i32 s2, 0x300
	s_cselect_b64 s[4:5], -1, 0
	s_cmpk_gt_i32 s2, 0x2ff
	v_readfirstlane_b32 s6, v164
	s_cbranch_scc1 .LBB0_146
	s_ashr_i32 s3, s2, 31
	s_lshr_b32 s3, s3, 29
	s_add_i32 s3, s2, s3
	s_ashr_i32 s7, s3, 3
	s_and_b32 s3, s3, -8
	s_sub_i32 s3, s2, s3
	s_cmp_lt_i32 s3, 0
	s_movk_i32 s18, 0x61
	s_cselect_b32 s18, s18, 0x60
	s_mul_i32 s3, s3, s18
	s_add_i32 s3, s3, s7
	s_mul_hi_i32 s7, s3, 0x2aaaaaab
	s_lshr_b32 s18, s7, 31
	s_ashr_i32 s7, s7, 4
	s_add_i32 s7, s7, s18
	s_lshl_b32 s18, s7, 2
	s_mulk_i32 s7, 0x60
	s_sub_i32 s3, s3, s7
	s_bfe_i32 s7, s3, 0x80000
	s_bfe_u32 s7, s7, 0x2000d
	s_add_i32 s7, s3, s7
	s_bfe_i32 s19, s7, 0x80000
	s_and_b32 s7, s7, 0xfc
	s_sub_i32 s3, s3, s7
	s_sext_i32_i16 s19, s19
	s_sext_i32_i8 s3, s3
	s_add_i32 s18, s18, s3
	s_ashr_i32 s70, s19, 2

; #define SEAM(k) do { if (IN(k) && hi > (k) + 1) xcd_barrier(xbar); } while (0)
; __global__ void __launch_bounds__(NTHREADS, 2) mk_fwd(Params P) {
;     ...
;         EpiPle<false> E{X1B, PP0, SLOTA, nullptr}; pg8::gemm_phase<EpiPle<false>, true>(lds, g, S, E);
;     }
;     SEAM(5);
.Lpb5_fast:
	global_atomic_add v250, v252, s[54:55] offset:12
	v_mov_b32_e32 v253, 0xb000
	global_atomic_add v253, v252, s[54:55]
	global_atomic_add v253, v252, s[54:55] offset:64
	global_atomic_add v253, v252, s[54:55] offset:128
	global_atomic_add v253, v252, s[54:55] offset:192
	global_atomic_add v253, v252, s[54:55] offset:256
	global_atomic_add v253, v252, s[54:55] offset:320
	global_atomic_add v253, v252, s[54:55] offset:384
	global_atomic_add v253, v252, s[54:55] offset:448
	v_mov_b32_e32 v253, 0x8200
	s_mov_b32 s99, 0

; __global__ void __launch_bounds__(NTHREADS, 2) mk_fwd(Params P) {
;     ...
;     if (IN(6)) {
;         pg8::Gemm g{SLOTA, WINB, MTOK, 8192, 2048, 1 << 30, 0}; pg8::StaticOrder S; S.init(MTOK, 8192, G, bid);
;         EpiL1In E{Qb, Kb, VTb, Zb, KPART}; pg8::gemm_phase<EpiL1In, true>(lds, g, S, E);
.LBB0_498:
	v_and_b32_e32 v251, 0xffffffc0, v164
	v_add_u32_e32 v251, 0xb000, v251
	global_load_dword v250, v251, s[54:55] sc1
	s_add_u32 s3, s40, 0x3c00000
	s_addc_u32 s76, s41, 0
	s_add_u32 s0, s40, 0xa000000
	s_addc_u32 s1, s41, 0
	s_cmp_lt_i32 s42, 7
	s_cselect_b64 s[6:7], -1, 0
	s_and_b64 s[16:17], s[6:7], s[4:5]
	s_andn2_b64 vcc, exec, s[16:17]
	s_cbranch_vccnz .LBB0_571
	s_cmpk_lt_i32 s2, 0x400
	s_cselect_b64 s[4:5], -1, 0
	s_cmpk_gt_i32 s2, 0x3ff
	v_readfirstlane_b32 s26, v164
	s_cbranch_scc1 .LBB0_505
	s_ashr_i32 s6, s2, 31
	s_lshr_b32 s6, s6, 29
	s_add_i32 s8, s2, s6
	s_and_b32 s6, s8, -8
	s_sub_i32 s9, s2, s6
	s_cmp_gt_i32 s9, -1
	s_cbranch_scc0 .LBB0_502
	s_lshl_b32 s10, s9, 7
	s_cbranch_execz .LBB0_503
	s_branch .LBB0_504
